# v8 + peeled first iteration also in the FFN-up GEMM loop (dataflow-selected first-touch MFMAs use srcC=0; its zeroing removed)
# speedup vs baseline: 1.0062x; 1.0005x over previous
; __device__ __forceinline__ const char* a_tile(const Gemm& g, const Unit& u) { return (const char*)(g.A + ((long)u.z1 * g.aS1 + (long)u.z2 * g.aS2 + (long)u.pm * BM * g.lda)); }
; __device__ __forceinline__ const char* b_tile(const Gemm& g, const Unit& u) { return (const char*)(g.Bt + ((long)u.z1 * g.bS1 + (long)u.z2 * g.bS2 + (long)u.pn * BM * g.ldb)); }
; #define PG8_WAIT_V(n) asm volatile("s_waitcnt vmcnt(" #n ")" ::: "memory")
; template <class Epi>
; __device__ __forceinline__ void gemm_phase(PG8_LAS unsigned char* lds, PG8_LAS unsigned char* xl, const Gemm g, const Sched& S, const Epi& E, const int wid) {
;     ...
;         const bool has_next = S.next(ui + 1, nxt);
;         const char* nA = has_next ? a_tile(g, nxt) : cA; const char* nB = has_next ? b_tile(g, nxt) : cB;
;         for (int t = 0; t < nt; t += 2) {
;             const bool last = (t == nt - 2);
;             const bool do0 = !blkdiag_v<Epi> || t == 0, do1 = !blkdiag_v<Epi> || t != 0;
;             long j1 = 0, ja2 = 0, jb2 = 0;
;             if constexpr (Epi::MID) {
;                 if (t == g.tj) { const int lnM = lane_id_opq(); E.mid(acc, cur, wr, wc, lnM & 15, lnM >> 4); }
;                 if (t >= g.tj) j1 = g.jA;
;                 if (t + 2 >= g.tj) { ja2 = g.jA; jb2 = g.jB; } }
;             const char* a1 = cA + (size_t)(t + 1) * kstep + j1;
;             const char* a2 = last ? nA : cA + (size_t)(t + 2) * kstep + ja2; const char* b2 = last ? nB : cB + (size_t)(t + 2) * kstep + jb2;
;             const char* a3 = a2 + kstep; const char* b3 = b2 + kstep;
;             PG8_LDB(B0, 0, 0); PG8_LDB(B1, 0, 1); PG8_SCHED; PG8_LDA(At, 0, 0); PG8_STAGE(PG8_SA(1, 1), a1 + hstepA, voffA);
;             PG8_WAIT_V(8); PG8_WAIT_L(0); PG8_BAR; if (do0) { PG8_MMA(0, 0, At, B0); PG8_MMA(0, 1, At, B1); } PG8_BAR; PG8_SCHED;
;             PG8_LDA(At, 0, 1); PG8_STAGE(PG8_SB(0, 0), b2, voffB); PG8_STAGE(PG8_SB(0, 1), b2 + hstepB, voffB); PG8_STAGE(PG8_SA(0, 0), a2, voffA);
;             PG8_WAIT_V(8); PG8_WAIT_L(0); PG8_BAR; if (do1) { PG8_MMA(1, 0, At, B0); PG8_MMA(1, 1, At, B1); } PG8_BAR; PG8_SCHED;
;     ...
; #pragma unroll
;         for (int a = 0; a < 2; ++a)
; #pragma unroll
;             for (int b = 0; b < 2; ++b)
; #pragma unroll
;                 for (int m = 0; m < 4; ++m)
; #pragma unroll
;                     for (int n = 0; n < 2; ++n) acc[a][b][m][n] = (f32x4){0.f, 0.f, 0.f, 0.f};
.LBB0_1105:
	s_ashr_i32 s51, s50, 31
	s_lshl_b64 s[8:9], s[50:51], 20
	s_add_u32 s56, s62, s8
	s_addc_u32 s57, s69, s9
	s_and_b64 s[8:9], s[46:47], exec
	s_cselect_b32 s8, s57, s45
	s_cselect_b32 s9, s56, s44
	s_ashr_i32 s49, s48, 31
	s_lshl_b64 s[10:11], s[48:49], 20
	s_add_u32 s58, s88, s10
	s_addc_u32 s59, s89, s11
	s_and_b64 s[10:11], s[46:47], exec
	s_cselect_b32 s49, s59, s77
	s_cselect_b32 s61, s58, s76
	s_add_u32 s72, s76, 0x100
	s_addc_u32 s73, s77, 0
	s_mov_b32 s54, -2
	s_cmp_lg_u32 s100, 1
	s_cbranch_scc1 .Ldefbar_skip_9
	s_mov_b32 s100, 0
	s_barrier
.Ldefbar_skip_9:
	v_add_u32_e32 v204, s22, v210
	v_add_u32_e32 v205, s22, v212
	v_add_u32_e32 v226, s22, v214
	v_add_u32_e32 v227, s22, v216
	v_add_u32_e32 v248, 0x10000, v195
	s_add_u32 s76, s44, 0x100
	s_addc_u32 s77, s45, 0
	s_add_i32 s55, 0, 0x10000
	s_cmp_eq_u32 s54, 28
	s_cselect_b32 s11, s8, s77
	s_cselect_b32 s10, s9, s76
	s_cselect_b32 vcc_hi, s49, s73
	s_cselect_b32 vcc_lo, s61, s72
	s_add_i32 s4, 0, 0x14000
	ds_read_b128 v[4:7], v248 offset:0
	ds_read_b128 v[8:11], v248 offset:1024
	ds_read_b128 v[84:87], v248 offset:2048
	ds_read_b128 v[88:91], v248 offset:3072
	ds_read_b128 v[92:95], v248 offset:16384
	ds_read_b128 v[96:99], v248 offset:17408
	ds_read_b128 v[100:103], v248 offset:18432
	ds_read_b128 v[104:107], v248 offset:19456
	s_add_i32 m0, s90, 0xc000
	ds_read_b128 v[108:111], v225
	ds_read_b128 v[172:175], v225 offset:1024
	ds_read_b128 v[176:179], v225 offset:2048
	ds_read_b128 v[180:183], v225 offset:3072
	ds_read_b128 v[184:187], v225 offset:4096
	ds_read_b128 v[188:191], v225 offset:5120
	ds_read_b128 v[230:233], v225 offset:6144
	ds_read_b128 v[234:237], v225 offset:7168
	global_load_lds_dwordx4 v218, s[44:45]
	s_add_i32 m0, s90, 0xe000
	s_nop 0
	global_load_lds_dwordx4 v220, s[44:45]
	s_waitcnt vmcnt(8)
	s_waitcnt lgkmcnt(0)
	s_setprio 1
	s_barrier
	v_mfma_f32_16x16x32_bf16 v[60:63], v[4:7], v[108:111], 0
	v_mfma_f32_16x16x32_bf16 v[64:67], v[84:87], v[108:111], 0
	v_mfma_f32_16x16x32_bf16 v[120:123], v[4:7], v[176:179], 0
	v_mfma_f32_16x16x32_bf16 v[124:127], v[84:87], v[176:179], 0
	v_mfma_f32_16x16x32_bf16 v[164:167], v[4:7], v[184:187], 0
	v_mfma_f32_16x16x32_bf16 v[160:163], v[84:87], v[184:187], 0
	v_mfma_f32_16x16x32_bf16 v[80:83], v[4:7], v[230:233], 0
	v_mfma_f32_16x16x32_bf16 v[128:131], v[84:87], v[230:233], 0
	v_mfma_f32_16x16x32_bf16 v[60:63], v[8:11], v[172:175], v[60:63]
	v_mfma_f32_16x16x32_bf16 v[64:67], v[88:91], v[172:175], v[64:67]
	v_mfma_f32_16x16x32_bf16 v[120:123], v[8:11], v[180:183], v[120:123]
	v_mfma_f32_16x16x32_bf16 v[124:127], v[88:91], v[180:183], v[124:127]
	v_mfma_f32_16x16x32_bf16 v[164:167], v[8:11], v[188:191], v[164:167]
	v_mfma_f32_16x16x32_bf16 v[160:163], v[88:91], v[188:191], v[160:163]
	v_mfma_f32_16x16x32_bf16 v[80:83], v[8:11], v[234:237], v[80:83]
	v_mfma_f32_16x16x32_bf16 v[128:131], v[88:91], v[234:237], v[128:131]
	s_setprio 0
	s_setprio 1
	v_mfma_f32_16x16x32_bf16 v[112:115], v[92:95], v[108:111], 0
	v_mfma_f32_16x16x32_bf16 v[108:111], v[100:103], v[108:111], 0
	v_mfma_f32_16x16x32_bf16 v[116:119], v[92:95], v[176:179], 0
	v_mfma_f32_16x16x32_bf16 v[156:159], v[96:99], v[180:183], v[116:119]
	v_mfma_f32_16x16x32_bf16 v[116:119], v[100:103], v[176:179], 0
	v_mfma_f32_16x16x32_bf16 v[152:155], v[104:107], v[180:183], v[116:119]
	v_mfma_f32_16x16x32_bf16 v[116:119], v[92:95], v[184:187], 0
	v_mfma_f32_16x16x32_bf16 v[148:151], v[96:99], v[188:191], v[116:119]
	v_mfma_f32_16x16x32_bf16 v[116:119], v[100:103], v[184:187], 0
	v_mfma_f32_16x16x32_bf16 v[144:147], v[104:107], v[188:191], v[116:119]
	v_mfma_f32_16x16x32_bf16 v[116:119], v[92:95], v[230:233], 0
	v_mfma_f32_16x16x32_bf16 v[140:143], v[96:99], v[234:237], v[116:119]
	v_mfma_f32_16x16x32_bf16 v[116:119], v[100:103], v[230:233], 0
	v_mfma_f32_16x16x32_bf16 v[112:115], v[96:99], v[172:175], v[112:115]
	v_mfma_f32_16x16x32_bf16 v[136:139], v[104:107], v[234:237], v[116:119]
	v_mfma_f32_16x16x32_bf16 v[108:111], v[104:107], v[172:175], v[108:111]
	s_barrier
	s_setprio 0
	s_add_i32 s5, s55, s29
	s_mov_b32 m0, s5
	ds_read_b128 v[116:119], v225 offset:16384
	ds_read_b128 v[172:175], v225 offset:17408
	ds_read_b128 v[176:179], v225 offset:18432
	ds_read_b128 v[180:183], v225 offset:19456
	ds_read_b128 v[184:187], v225 offset:20480
	ds_read_b128 v[188:191], v225 offset:21504
	ds_read_b128 v[230:233], v225 offset:22528
	ds_read_b128 v[234:237], v225 offset:23552
	global_load_lds_dwordx4 v212, vcc
	s_add_i32 m0, s5, 0x2000
	s_add_u32 s44, vcc_lo, 0x80000
	s_addc_u32 s45, vcc_hi, 0
	s_add_i32 s4, s4, s29
	global_load_lds_dwordx4 v216, vcc
	s_mov_b32 m0, s4
	s_nop 0
	global_load_lds_dwordx4 v212, s[44:45]
	s_add_i32 m0, s4, 0x2000
	s_nop 0
	global_load_lds_dwordx4 v216, s[44:45]
	s_mov_b32 m0, s90
	s_nop 0
	global_load_lds_dwordx4 v210, s[10:11]
	s_mov_b32 m0, s13
	s_nop 0
	global_load_lds_dwordx4 v214, s[10:11]
	s_waitcnt vmcnt(8)
	s_waitcnt lgkmcnt(0)
	s_setprio 1
	s_barrier
; #define PG8_STAGE(bufoff, gbase, voff) do { _Pragma("unroll") for (int _i = 0; _i < 2; ++_i) \
;         __builtin_amdgcn_global_load_lds((const unsigned*)((const char*)(gbase) + (voff)[_i]), (PG8_LAS unsigned*)(lds + (bufoff) + ldsw + _i * 8192), 16, 0, 0); } while (0)
; #define PG8_LDA(dst, b, h) do { _Pragma("unroll") for (int m = 0; m < 4; ++m) _Pragma("unroll") for (int k = 0; k < 2; ++k) dst[m][k] = *(const PG8_LAS bf16x8*)(lds + PG8_SA(b, h) + aoff + m * 2048 + k * 1024); } while (0)
; #define PG8_LDB(dst, b, h) do { _Pragma("unroll") for (int n = 0; n < 2; ++n) _Pragma("unroll") for (int k = 0; k < 2; ++k) dst[n][k] = *(const PG8_LAS bf16x8*)(lds + PG8_SB(b, h) + boff + n * 2048 + k * 1024); } while (0)
; #define PG8_MMA(ai, bj, At, Bt) do { __builtin_amdgcn_s_setprio(1); _Pragma("unroll") for (int m = 0; m < 4; ++m) _Pragma("unroll") for (int n = 0; n < 2; ++n) _Pragma("unroll") for (int k = 0; k < 2; ++k) \
;         acc[ai][bj][m][n] = __builtin_amdgcn_mfma_f32_16x16x32_bf16(Bt[n][k], At[m][k], acc[ai][bj][m][n], 0, 0, 0); __builtin_amdgcn_s_setprio(0); } while (0)
; #define PG8_WAIT_V(n) asm volatile("s_waitcnt vmcnt(" #n ")" ::: "memory")
; #define PG8_WAIT_L(n) asm volatile("s_waitcnt lgkmcnt(" #n ")" ::: "memory")
; #define PG8_BAR __builtin_amdgcn_s_barrier()
; #define PG8_SCHED __builtin_amdgcn_sched_barrier(0)
; template <class Epi>
; __device__ __forceinline__ void gemm_phase(PG8_LAS unsigned char* lds, PG8_LAS unsigned char* xl, const Gemm g, const Sched& S, const Epi& E, const int wid) {
;     ...
;             PG8_WAIT_V(8); PG8_WAIT_L(0); PG8_BAR; if (do1) { PG8_MMA(1, 0, At, B0); PG8_MMA(1, 1, At, B1); } PG8_BAR; PG8_SCHED;
;             PG8_LDB(B0, 1, 0); PG8_LDB(B1, 1, 1); PG8_SCHED; PG8_LDA(At, 1, 0); PG8_STAGE(PG8_SA(0, 1), a2 + hstepA, voffA);
;             PG8_WAIT_V(8); PG8_WAIT_L(0); PG8_BAR; if (do0) { PG8_MMA(0, 0, At, B0); PG8_MMA(0, 1, At, B1); } PG8_BAR; PG8_SCHED;
;             PG8_LDA(At, 1, 1); PG8_STAGE(PG8_SB(1, 0), b3, voffB); PG8_STAGE(PG8_SB(1, 1), b3 + hstepB, voffB); PG8_STAGE(PG8_SA(1, 0), a3, voffA);
;             PG8_WAIT_V(8); PG8_WAIT_L(0); PG8_BAR; if (do1) { PG8_MMA(1, 0, At, B0); PG8_MMA(1, 1, At, B1); } PG8_BAR; PG8_SCHED;
	v_mfma_f32_16x16x32_bf16 v[132:135], v[4:7], v[116:119], 0
	v_mfma_f32_16x16x32_bf16 v[68:71], v[84:87], v[116:119], 0
	v_mfma_f32_16x16x32_bf16 v[56:59], v[4:7], v[176:179], 0
	v_mfma_f32_16x16x32_bf16 v[52:55], v[84:87], v[176:179], 0
	v_mfma_f32_16x16x32_bf16 v[40:43], v[4:7], v[184:187], 0
	v_mfma_f32_16x16x32_bf16 v[36:39], v[84:87], v[184:187], 0
	v_mfma_f32_16x16x32_bf16 v[4:7], v[4:7], v[230:233], 0
	v_mfma_f32_16x16x32_bf16 v[132:135], v[8:11], v[172:175], v[132:135]
	v_mfma_f32_16x16x32_bf16 v[68:71], v[88:91], v[172:175], v[68:71]
	v_mfma_f32_16x16x32_bf16 v[56:59], v[8:11], v[180:183], v[56:59]
	v_mfma_f32_16x16x32_bf16 v[52:55], v[88:91], v[180:183], v[52:55]
	v_mfma_f32_16x16x32_bf16 v[40:43], v[8:11], v[188:191], v[40:43]
	v_mfma_f32_16x16x32_bf16 v[36:39], v[88:91], v[188:191], v[36:39]
	v_mfma_f32_16x16x32_bf16 v[4:7], v[8:11], v[234:237], v[4:7]
	v_mfma_f32_16x16x32_bf16 v[8:11], v[84:87], v[230:233], 0
	v_mfma_f32_16x16x32_bf16 v[8:11], v[88:91], v[234:237], v[8:11]
	s_setprio 0
	s_setprio 1
	v_mfma_f32_16x16x32_bf16 v[48:51], v[92:95], v[116:119], 0
	v_mfma_f32_16x16x32_bf16 v[44:47], v[100:103], v[116:119], 0
	v_mfma_f32_16x16x32_bf16 v[32:35], v[92:95], v[176:179], 0
	v_mfma_f32_16x16x32_bf16 v[28:31], v[100:103], v[176:179], 0
	v_mfma_f32_16x16x32_bf16 v[24:27], v[92:95], v[184:187], 0
	v_mfma_f32_16x16x32_bf16 v[20:23], v[100:103], v[184:187], 0
	v_mfma_f32_16x16x32_bf16 v[16:19], v[92:95], v[230:233], 0
	v_mfma_f32_16x16x32_bf16 v[12:15], v[100:103], v[230:233], 0
	v_mfma_f32_16x16x32_bf16 v[48:51], v[96:99], v[172:175], v[48:51]
	v_mfma_f32_16x16x32_bf16 v[44:47], v[104:107], v[172:175], v[44:47]
	v_mfma_f32_16x16x32_bf16 v[32:35], v[96:99], v[180:183], v[32:35]
	v_mfma_f32_16x16x32_bf16 v[28:31], v[104:107], v[180:183], v[28:31]
	v_mfma_f32_16x16x32_bf16 v[24:27], v[96:99], v[188:191], v[24:27]
	v_mfma_f32_16x16x32_bf16 v[20:23], v[104:107], v[188:191], v[20:23]
	v_mfma_f32_16x16x32_bf16 v[16:19], v[96:99], v[234:237], v[16:19]
	v_mfma_f32_16x16x32_bf16 v[12:15], v[104:107], v[234:237], v[12:15]
	s_barrier
	s_setprio 0
	s_add_i32 s4, 0, 0x18000
	s_add_i32 s5, 0, 0x1c000
	ds_read_b128 v[72:75], v248 offset:32768
	ds_read_b128 v[84:87], v248 offset:33792
	ds_read_b128 v[88:91], v248 offset:34816
	ds_read_b128 v[92:95], v248 offset:35840
	ds_read_b128 v[96:99], v248 offset:49152
	ds_read_b128 v[100:103], v248 offset:50176
	ds_read_b128 v[104:107], v248 offset:51200
	ds_read_b128 v[172:175], v248 offset:52224
	s_add_u32 s100, s10, 0x80000
	s_addc_u32 s101, s11, 0
	s_mov_b32 m0, s91
	ds_read_b128 v[116:119], v225 offset:32768
	ds_read_b128 v[168:171], v225 offset:33792
	ds_read_b128 v[176:179], v225 offset:34816
	ds_read_b128 v[180:183], v225 offset:35840
	ds_read_b128 v[184:187], v225 offset:36864
	ds_read_b128 v[188:191], v225 offset:37888
	ds_read_b128 v[230:233], v225 offset:38912
	ds_read_b128 v[234:237], v225 offset:39936
	global_load_lds_dwordx4 v210, s[100:101]
	s_mov_b32 m0, s92
	s_nop 0
	global_load_lds_dwordx4 v214, s[100:101]
	s_waitcnt vmcnt(8)
	s_waitcnt lgkmcnt(0)
	s_setprio 1
	s_barrier
	v_mfma_f32_16x16x32_bf16 v[60:63], v[72:75], v[116:119], v[60:63]
	v_mfma_f32_16x16x32_bf16 v[64:67], v[88:91], v[116:119], v[64:67]
	v_mfma_f32_16x16x32_bf16 v[120:123], v[72:75], v[176:179], v[120:123]
	v_mfma_f32_16x16x32_bf16 v[124:127], v[88:91], v[176:179], v[124:127]
	v_mfma_f32_16x16x32_bf16 v[164:167], v[72:75], v[184:187], v[164:167]
	v_mfma_f32_16x16x32_bf16 v[160:163], v[88:91], v[184:187], v[160:163]
	v_mfma_f32_16x16x32_bf16 v[80:83], v[72:75], v[230:233], v[80:83]
	v_mfma_f32_16x16x32_bf16 v[128:131], v[88:91], v[230:233], v[128:131]
	v_mfma_f32_16x16x32_bf16 v[60:63], v[84:87], v[168:171], v[60:63]
	v_mfma_f32_16x16x32_bf16 v[64:67], v[92:95], v[168:171], v[64:67]
	v_mfma_f32_16x16x32_bf16 v[120:123], v[84:87], v[180:183], v[120:123]
	v_mfma_f32_16x16x32_bf16 v[124:127], v[92:95], v[180:183], v[124:127]
	v_mfma_f32_16x16x32_bf16 v[164:167], v[84:87], v[188:191], v[164:167]
	v_mfma_f32_16x16x32_bf16 v[160:163], v[92:95], v[188:191], v[160:163]
	v_mfma_f32_16x16x32_bf16 v[80:83], v[84:87], v[234:237], v[80:83]
	v_mfma_f32_16x16x32_bf16 v[128:131], v[92:95], v[234:237], v[128:131]
	s_setprio 0
	s_setprio 1
	v_mfma_f32_16x16x32_bf16 v[108:111], v[104:107], v[116:119], v[108:111]
	v_mfma_f32_16x16x32_bf16 v[112:115], v[96:99], v[116:119], v[112:115]
	v_mfma_f32_16x16x32_bf16 v[116:119], v[172:175], v[168:171], v[108:111]
	v_mfma_f32_16x16x32_bf16 v[108:111], v[96:99], v[176:179], v[156:159]
	v_mfma_f32_16x16x32_bf16 v[156:159], v[100:103], v[180:183], v[108:111]
	v_mfma_f32_16x16x32_bf16 v[108:111], v[104:107], v[176:179], v[152:155]
	v_mfma_f32_16x16x32_bf16 v[152:155], v[172:175], v[180:183], v[108:111]
	v_mfma_f32_16x16x32_bf16 v[108:111], v[96:99], v[184:187], v[148:151]
	v_mfma_f32_16x16x32_bf16 v[148:151], v[100:103], v[188:191], v[108:111]
	v_mfma_f32_16x16x32_bf16 v[108:111], v[104:107], v[184:187], v[144:147]
	v_mfma_f32_16x16x32_bf16 v[144:147], v[172:175], v[188:191], v[108:111]
	v_mfma_f32_16x16x32_bf16 v[108:111], v[96:99], v[230:233], v[140:143]
	v_mfma_f32_16x16x32_bf16 v[140:143], v[100:103], v[234:237], v[108:111]
	v_mfma_f32_16x16x32_bf16 v[108:111], v[104:107], v[230:233], v[136:139]
	v_mfma_f32_16x16x32_bf16 v[112:115], v[100:103], v[168:171], v[112:115]
	v_mfma_f32_16x16x32_bf16 v[136:139], v[172:175], v[234:237], v[108:111]
	s_barrier
; #define PG8_STAGE(bufoff, gbase, voff) do { _Pragma("unroll") for (int _i = 0; _i < 2; ++_i) \
;         __builtin_amdgcn_global_load_lds((const unsigned*)((const char*)(gbase) + (voff)[_i]), (PG8_LAS unsigned*)(lds + (bufoff) + ldsw + _i * 8192), 16, 0, 0); } while (0)
; #define PG8_LDA(dst, b, h) do { _Pragma("unroll") for (int m = 0; m < 4; ++m) _Pragma("unroll") for (int k = 0; k < 2; ++k) dst[m][k] = *(const PG8_LAS bf16x8*)(lds + PG8_SA(b, h) + aoff + m * 2048 + k * 1024); } while (0)
; #define PG8_MMA(ai, bj, At, Bt) do { __builtin_amdgcn_s_setprio(1); _Pragma("unroll") for (int m = 0; m < 4; ++m) _Pragma("unroll") for (int n = 0; n < 2; ++n) _Pragma("unroll") for (int k = 0; k < 2; ++k) \
;         acc[ai][bj][m][n] = __builtin_amdgcn_mfma_f32_16x16x32_bf16(Bt[n][k], At[m][k], acc[ai][bj][m][n], 0, 0, 0); __builtin_amdgcn_s_setprio(0); } while (0)
; #define PG8_WAIT_V(n) asm volatile("s_waitcnt vmcnt(" #n ")" ::: "memory")
; #define PG8_WAIT_L(n) asm volatile("s_waitcnt lgkmcnt(" #n ")" ::: "memory")
; #define PG8_BAR __builtin_amdgcn_s_barrier()
; #define PG8_SCHED __builtin_amdgcn_sched_barrier(0)
; template <class Epi>
; __device__ __forceinline__ void gemm_phase(PG8_LAS unsigned char* lds, PG8_LAS unsigned char* xl, const Gemm g, const Sched& S, const Epi& E, const int wid) {
;     ...
;             PG8_LDA(At, 1, 1); PG8_STAGE(PG8_SB(1, 0), b3, voffB); PG8_STAGE(PG8_SB(1, 1), b3 + hstepB, voffB); PG8_STAGE(PG8_SA(1, 0), a3, voffA);
;             PG8_WAIT_V(8); PG8_WAIT_L(0); PG8_BAR; if (do1) { PG8_MMA(1, 0, At, B0); PG8_MMA(1, 1, At, B1); } PG8_BAR; PG8_SCHED;
;         }
	s_setprio 0
	s_add_i32 s4, s4, s29
	s_mov_b32 m0, s4
	s_nop 0
	ds_read_b128 v[108:111], v225 offset:49152
	ds_read_b128 v[176:179], v225 offset:50176
	ds_read_b128 v[180:183], v225 offset:51200
	ds_read_b128 v[184:187], v225 offset:52224
	ds_read_b128 v[188:191], v225 offset:53248
	ds_read_b128 v[230:233], v225 offset:54272
	ds_read_b128 v[234:237], v225 offset:55296
	ds_read_b128 v[238:241], v225 offset:56320
	global_load_lds_dwordx4 v205, vcc
	s_add_i32 m0, s4, 0x2000
	s_add_u32 s100, vcc_lo, 0x80080
	global_load_lds_dwordx4 v227, vcc
	s_addc_u32 s101, vcc_hi, 0
	s_add_i32 s4, s5, s29
	s_mov_b32 m0, s4
	s_nop 0
	global_load_lds_dwordx4 v212, s[100:101]
	s_add_i32 m0, s4, 0x2000
	s_nop 0
	global_load_lds_dwordx4 v216, s[100:101]
	s_mov_b32 m0, s40
	s_nop 0
	global_load_lds_dwordx4 v204, s[10:11]
	s_mov_b32 m0, s41
	s_nop 0
	global_load_lds_dwordx4 v226, s[10:11]
	s_waitcnt vmcnt(8)
	s_waitcnt lgkmcnt(0)
	s_setprio 1
	s_barrier
	v_mfma_f32_16x16x32_bf16 v[4:7], v[72:75], v[234:237], v[4:7]
	v_mfma_f32_16x16x32_bf16 v[132:135], v[72:75], v[108:111], v[132:135]
	v_mfma_f32_16x16x32_bf16 v[68:71], v[88:91], v[108:111], v[68:71]
	v_mfma_f32_16x16x32_bf16 v[56:59], v[72:75], v[180:183], v[56:59]
	v_mfma_f32_16x16x32_bf16 v[52:55], v[88:91], v[180:183], v[52:55]
	v_mfma_f32_16x16x32_bf16 v[40:43], v[72:75], v[188:191], v[40:43]
	v_mfma_f32_16x16x32_bf16 v[36:39], v[88:91], v[188:191], v[36:39]
	v_mfma_f32_16x16x32_bf16 v[168:171], v[84:87], v[238:241], v[4:7]
	v_mfma_f32_16x16x32_bf16 v[4:7], v[88:91], v[234:237], v[8:11]
	v_mfma_f32_16x16x32_bf16 v[132:135], v[84:87], v[176:179], v[132:135]
	v_mfma_f32_16x16x32_bf16 v[68:71], v[92:95], v[176:179], v[68:71]
	v_mfma_f32_16x16x32_bf16 v[56:59], v[84:87], v[184:187], v[56:59]
	v_mfma_f32_16x16x32_bf16 v[52:55], v[92:95], v[184:187], v[52:55]
	v_mfma_f32_16x16x32_bf16 v[40:43], v[84:87], v[230:233], v[40:43]
	v_mfma_f32_16x16x32_bf16 v[36:39], v[92:95], v[230:233], v[36:39]
	v_mfma_f32_16x16x32_bf16 v[72:75], v[92:95], v[238:241], v[4:7]
	s_setprio 0
	s_setprio 1
	v_mfma_f32_16x16x32_bf16 v[4:7], v[96:99], v[108:111], v[48:51]
	v_mfma_f32_16x16x32_bf16 v[48:51], v[100:103], v[176:179], v[4:7]
	v_mfma_f32_16x16x32_bf16 v[4:7], v[104:107], v[108:111], v[44:47]
	v_mfma_f32_16x16x32_bf16 v[44:47], v[172:175], v[176:179], v[4:7]
	v_mfma_f32_16x16x32_bf16 v[4:7], v[96:99], v[180:183], v[32:35]
	v_mfma_f32_16x16x32_bf16 v[32:35], v[100:103], v[184:187], v[4:7]
	v_mfma_f32_16x16x32_bf16 v[4:7], v[104:107], v[180:183], v[28:31]
	v_mfma_f32_16x16x32_bf16 v[28:31], v[172:175], v[184:187], v[4:7]
	v_mfma_f32_16x16x32_bf16 v[4:7], v[96:99], v[188:191], v[24:27]
	v_mfma_f32_16x16x32_bf16 v[24:27], v[100:103], v[230:233], v[4:7]
	v_mfma_f32_16x16x32_bf16 v[4:7], v[104:107], v[188:191], v[20:23]
	v_mfma_f32_16x16x32_bf16 v[20:23], v[172:175], v[230:233], v[4:7]
	v_mfma_f32_16x16x32_bf16 v[4:7], v[96:99], v[234:237], v[16:19]
	v_mfma_f32_16x16x32_bf16 v[16:19], v[100:103], v[238:241], v[4:7]
	v_mfma_f32_16x16x32_bf16 v[4:7], v[104:107], v[234:237], v[12:15]
	v_mfma_f32_16x16x32_bf16 v[12:15], v[172:175], v[238:241], v[4:7]
	s_barrier
	s_setprio 0
	s_add_i32 s54, s54, 2
	s_add_u32 s72, s72, 0x100
	s_addc_u32 s73, s73, 0
	s_cmp_gt_u32 s54, 29
	s_mov_b64 s[44:45], s[76:77]
